# XCD grid barrier: non-leader workgroups poll the top-level generation word directly (one memory hop less per barrier exit) and leaders no longer republish it per XCD; also carries the GEMM2 epilogue l
# speedup vs baseline: 1.0085x; 1.0085x over previous
.LBB0_99:
	s_or_b64 exec, exec, s[8:9]
	v_cvt_f32_u32_e32 v4, v2
	s_waitcnt vmcnt(0)
	v_readfirstlane_b32 s2, v3
	v_sub_u32_e32 v3, 0, v2
	v_rcp_iflag_f32_e32 v4, v4
	v_add_u32_e32 v5, s2, v1
	v_mul_f32_e32 v4, 0x4f7ffffe, v4
	v_cvt_u32_f32_e32 v4, v4
	v_mul_lo_u32 v1, v3, v4
	v_mul_hi_u32 v1, v4, v1
	v_add_u32_e32 v1, v4, v1
	v_mul_hi_u32 v1, v5, v1
	v_mul_lo_u32 v3, v1, v2
	v_sub_u32_e32 v3, v5, v3
	v_add_u32_e32 v4, 1, v1
	v_cmp_ge_u32_e32 vcc, v3, v2
	s_nop 1
	v_cndmask_b32_e32 v1, v1, v4, vcc
	v_sub_u32_e32 v4, v3, v2
	v_cndmask_b32_e32 v3, v3, v4, vcc
	v_add_u32_e32 v4, 1, v1
	v_cmp_ge_u32_e32 vcc, v3, v2
	v_add_u32_e32 v3, 1, v5
	s_nop 0
	v_cndmask_b32_e32 v1, v1, v4, vcc
	v_mul_lo_u32 v4, v2, v1
	v_add_u32_e32 v2, v4, v2
	v_cmp_ne_u32_e32 vcc, v3, v2
	s_and_saveexec_b64 s[2:3], vcc
	s_xor_b64 s[6:7], exec, s[2:3]
	s_cbranch_execz .LBB0_113
	s_waitcnt lgkmcnt(0)
	v_mov_b32_e32 v0, 0
	s_add_u32 s12, s82, 0x2a163500
	s_addc_u32 s13, s83, 0
	global_load_dword v0, v0, s[12:13] sc1
	s_waitcnt vmcnt(0)
	v_cmp_eq_u32_e32 vcc, v0, v1
	s_and_saveexec_b64 s[8:9], vcc
	s_cbranch_execz .LBB0_112
	s_add_u32 s10, s82, 0x2a160200
	s_addc_u32 s11, s83, 0
	s_mov_b32 s2, 1
	s_mov_b64 s[14:15], 0
	v_mov_b32_e32 v0, 0
	s_branch .LBB0_103

.LBB0_130:
	s_or_b64 exec, exec, s[6:7]
	s_mov_b64 s[6:7], exec
	v_mbcnt_lo_u32_b32 v0, s6, 0
	v_mbcnt_hi_u32_b32 v0, s7, v0
	v_cmp_eq_u32_e32 vcc, 0, v0
	s_waitcnt vmcnt(0)
	buffer_inv sc1
	s_and_saveexec_b64 s[8:9], vcc
	s_cbranch_execz .LBB0_132
	s_bcnt1_i32_b64 s2, s[6:7]
	v_mov_b32_e32 v0, 0x2000
	v_mov_b32_e32 v1, s2
.LBB0_132:
	s_or_b64 exec, exec, s[8:9]
	s_waitcnt vmcnt(0)

.LBB0_221:
	s_or_b64 exec, exec, s[8:9]
	v_cvt_f32_u32_e32 v4, v2
	s_waitcnt vmcnt(0)
	v_readfirstlane_b32 s2, v3
	v_sub_u32_e32 v3, 0, v2
	v_rcp_iflag_f32_e32 v4, v4
	v_add_u32_e32 v5, s2, v1
	v_mul_f32_e32 v4, 0x4f7ffffe, v4
	v_cvt_u32_f32_e32 v4, v4
	v_mul_lo_u32 v1, v3, v4
	v_mul_hi_u32 v1, v4, v1
	v_add_u32_e32 v1, v4, v1
	v_mul_hi_u32 v1, v5, v1
	v_mul_lo_u32 v3, v1, v2
	v_sub_u32_e32 v3, v5, v3
	v_add_u32_e32 v4, 1, v1
	v_cmp_ge_u32_e32 vcc, v3, v2
	s_nop 1
	v_cndmask_b32_e32 v1, v1, v4, vcc
	v_sub_u32_e32 v4, v3, v2
	v_cndmask_b32_e32 v3, v3, v4, vcc
	v_add_u32_e32 v4, 1, v1
	v_cmp_ge_u32_e32 vcc, v3, v2
	v_add_u32_e32 v3, 1, v5
	s_nop 0
	v_cndmask_b32_e32 v1, v1, v4, vcc
	v_mul_lo_u32 v4, v2, v1
	v_add_u32_e32 v2, v4, v2
	v_cmp_ne_u32_e32 vcc, v3, v2
	s_and_saveexec_b64 s[2:3], vcc
	s_xor_b64 s[6:7], exec, s[2:3]
	s_cbranch_execz .LBB0_235
	s_waitcnt lgkmcnt(0)
	v_mov_b32_e32 v0, 0
	s_add_u32 s12, s82, 0x2a163500
	s_addc_u32 s13, s83, 0
	global_load_dword v0, v0, s[12:13] sc1
	s_waitcnt vmcnt(0)
	v_cmp_eq_u32_e32 vcc, v0, v1
	s_and_saveexec_b64 s[8:9], vcc
	s_cbranch_execz .LBB0_234
	s_add_u32 s10, s82, 0x2a160200
	s_addc_u32 s11, s83, 0
	s_mov_b32 s2, 1
	s_mov_b64 s[18:19], 0
	v_mov_b32_e32 v0, 0
	s_branch .LBB0_225

.LBB0_252:
	s_or_b64 exec, exec, s[6:7]
	s_mov_b64 s[6:7], exec
	v_mbcnt_lo_u32_b32 v0, s6, 0
	v_mbcnt_hi_u32_b32 v0, s7, v0
	v_cmp_eq_u32_e32 vcc, 0, v0
	s_waitcnt vmcnt(0)
	buffer_inv sc1
	s_and_saveexec_b64 s[8:9], vcc
	s_cbranch_execz .LBB0_254
	s_bcnt1_i32_b64 s2, s[6:7]
	v_mov_b32_e32 v0, 0x2000
	v_mov_b32_e32 v1, s2
.LBB0_254:
	s_or_b64 exec, exec, s[8:9]
	s_waitcnt vmcnt(0)

.LBB0_404:
	s_or_b64 exec, exec, s[6:7]
	s_mov_b64 s[6:7], exec
	v_mbcnt_lo_u32_b32 v0, s6, 0
	v_mbcnt_hi_u32_b32 v0, s7, v0
	v_cmp_eq_u32_e32 vcc, 0, v0
	s_waitcnt vmcnt(0)
	buffer_inv sc1
	s_and_saveexec_b64 s[8:9], vcc
	s_cbranch_execz .LBB0_406
	s_bcnt1_i32_b64 s2, s[6:7]
	v_mov_b32_e32 v0, 0x2000
	v_mov_b32_e32 v1, s2
.LBB0_406:
	s_or_b64 exec, exec, s[8:9]
	s_waitcnt vmcnt(0)

.LBB0_593:
	s_or_b64 exec, exec, s[6:7]
	s_mov_b64 s[6:7], exec
	v_mbcnt_lo_u32_b32 v0, s6, 0
	v_mbcnt_hi_u32_b32 v0, s7, v0
	v_cmp_eq_u32_e32 vcc, 0, v0
	s_waitcnt vmcnt(0)
	buffer_inv sc1
	s_and_saveexec_b64 s[8:9], vcc
	s_cbranch_execz .LBB0_595
	s_bcnt1_i32_b64 s2, s[6:7]
	v_mov_b32_e32 v0, 0x2000
	v_mov_b32_e32 v1, s2
.LBB0_595:
	s_or_b64 exec, exec, s[8:9]
	s_waitcnt vmcnt(0)

.LBB0_665:
	s_or_b64 exec, exec, s[6:7]
	s_mov_b64 s[6:7], exec
	v_mbcnt_lo_u32_b32 v0, s6, 0
	v_mbcnt_hi_u32_b32 v0, s7, v0
	v_cmp_eq_u32_e32 vcc, 0, v0
	s_waitcnt vmcnt(0)
	buffer_inv sc1
	s_and_saveexec_b64 s[8:9], vcc
	s_cbranch_execz .LBB0_667
	s_bcnt1_i32_b64 s2, s[6:7]
	v_mov_b32_e32 v0, 0x2000
	v_mov_b32_e32 v1, s2
.LBB0_667:
	s_or_b64 exec, exec, s[8:9]
	s_waitcnt vmcnt(0)

.LBB0_730:
	s_or_b64 exec, exec, s[10:11]
	v_cvt_f32_u32_e32 v4, v2
	s_waitcnt vmcnt(0)
	v_readfirstlane_b32 s2, v3
	v_sub_u32_e32 v3, 0, v2
	v_rcp_iflag_f32_e32 v4, v4
	v_add_u32_e32 v5, s2, v1
	v_mul_f32_e32 v4, 0x4f7ffffe, v4
	v_cvt_u32_f32_e32 v4, v4
	v_mul_lo_u32 v1, v3, v4
	v_mul_hi_u32 v1, v4, v1
	v_add_u32_e32 v1, v4, v1
	v_mul_hi_u32 v1, v5, v1
	v_mul_lo_u32 v3, v1, v2
	v_sub_u32_e32 v3, v5, v3
	v_add_u32_e32 v4, 1, v1
	v_cmp_ge_u32_e32 vcc, v3, v2
	s_nop 1
	v_cndmask_b32_e32 v1, v1, v4, vcc
	v_sub_u32_e32 v4, v3, v2
	v_cndmask_b32_e32 v3, v3, v4, vcc
	v_add_u32_e32 v4, 1, v1
	v_cmp_ge_u32_e32 vcc, v3, v2
	v_add_u32_e32 v3, 1, v5
	s_nop 0
	v_cndmask_b32_e32 v1, v1, v4, vcc
	v_mul_lo_u32 v4, v2, v1
	v_add_u32_e32 v2, v4, v2
	v_cmp_ne_u32_e32 vcc, v3, v2
	s_and_saveexec_b64 s[2:3], vcc
	s_xor_b64 s[8:9], exec, s[2:3]
	s_cbranch_execz .LBB0_744
	s_waitcnt lgkmcnt(0)
	v_mov_b32_e32 v0, 0
	s_add_u32 s14, s82, 0x2a163500
	s_addc_u32 s15, s83, 0
	global_load_dword v0, v0, s[14:15] sc1
	s_waitcnt vmcnt(0)
	v_cmp_eq_u32_e32 vcc, v0, v1
	s_and_saveexec_b64 s[10:11], vcc
	s_cbranch_execz .LBB0_743
	s_add_u32 s12, s82, 0x2a160200
	s_addc_u32 s13, s83, 0
	s_mov_b32 s2, 1
	s_mov_b64 s[16:17], 0
	v_mov_b32_e32 v0, 0
	s_branch .LBB0_734

.LBB0_761:
	s_or_b64 exec, exec, s[8:9]
	s_mov_b64 s[8:9], exec
	v_mbcnt_lo_u32_b32 v0, s8, 0
	v_mbcnt_hi_u32_b32 v0, s9, v0
	v_cmp_eq_u32_e32 vcc, 0, v0
	s_waitcnt vmcnt(0)
	buffer_inv sc1
	s_and_saveexec_b64 s[10:11], vcc
	s_cbranch_execz .LBB0_763
	s_bcnt1_i32_b64 s2, s[8:9]
	v_mov_b32_e32 v0, 0x2000
	v_mov_b32_e32 v1, s2
.LBB0_763:
	s_or_b64 exec, exec, s[10:11]
	s_waitcnt vmcnt(0)

.LBB0_822:
	s_or_b64 exec, exec, s[8:9]
	v_cvt_f32_u32_e32 v4, v2
	s_waitcnt vmcnt(0)
	v_readfirstlane_b32 s2, v3
	v_sub_u32_e32 v3, 0, v2
	v_rcp_iflag_f32_e32 v4, v4
	v_add_u32_e32 v5, s2, v1
	v_mul_f32_e32 v4, 0x4f7ffffe, v4
	v_cvt_u32_f32_e32 v4, v4
	v_mul_lo_u32 v1, v3, v4
	v_mul_hi_u32 v1, v4, v1
	v_add_u32_e32 v1, v4, v1
	v_mul_hi_u32 v1, v5, v1
	v_mul_lo_u32 v3, v1, v2
	v_sub_u32_e32 v3, v5, v3
	v_add_u32_e32 v4, 1, v1
	v_cmp_ge_u32_e32 vcc, v3, v2
	s_nop 1
	v_cndmask_b32_e32 v1, v1, v4, vcc
	v_sub_u32_e32 v4, v3, v2
	v_cndmask_b32_e32 v3, v3, v4, vcc
	v_add_u32_e32 v4, 1, v1
	v_cmp_ge_u32_e32 vcc, v3, v2
	v_add_u32_e32 v3, 1, v5
	s_nop 0
	v_cndmask_b32_e32 v1, v1, v4, vcc
	v_mul_lo_u32 v4, v2, v1
	v_add_u32_e32 v2, v4, v2
	v_cmp_ne_u32_e32 vcc, v3, v2
	s_and_saveexec_b64 s[2:3], vcc
	s_xor_b64 s[6:7], exec, s[2:3]
	s_cbranch_execz .LBB0_836
	s_waitcnt lgkmcnt(0)
	v_mov_b32_e32 v0, 0
	s_add_u32 s16, s82, 0x2a163500
	s_addc_u32 s17, s83, 0
	global_load_dword v0, v0, s[16:17] sc1
	s_waitcnt vmcnt(0)
	v_cmp_eq_u32_e32 vcc, v0, v1
	s_and_saveexec_b64 s[8:9], vcc
	s_cbranch_execz .LBB0_835
	s_add_u32 s14, s82, 0x2a160200
	s_addc_u32 s15, s83, 0
	s_mov_b32 s2, 1
	s_mov_b64 s[18:19], 0
	v_mov_b32_e32 v0, 0
	s_branch .LBB0_826

.LBB0_853:
	s_or_b64 exec, exec, s[6:7]
	s_mov_b64 s[6:7], exec
	v_mbcnt_lo_u32_b32 v0, s6, 0
	v_mbcnt_hi_u32_b32 v0, s7, v0
	v_cmp_eq_u32_e32 vcc, 0, v0
	s_waitcnt vmcnt(0)
	buffer_inv sc1
	s_and_saveexec_b64 s[8:9], vcc
	s_cbranch_execz .LBB0_855
	s_bcnt1_i32_b64 s2, s[6:7]
	v_mov_b32_e32 v0, 0x2000
	v_mov_b32_e32 v1, s2
.LBB0_855:
	s_or_b64 exec, exec, s[8:9]
	s_waitcnt vmcnt(0)
